# x-attn fence without L2 writeback (same-CU handoff); P0 absmax loops streamed
# speedup vs baseline: 1.1191x; 1.0192x over previous
.LBB0_7:
.LBB0_8:
	s_movk_i32 s17, 0x5800
	s_mul_hi_i32 s2, s18, 0x2e8ba2e9
	s_lshr_b32 s3, s2, 31
	s_ashr_i32 s2, s2, 5
	s_add_i32 s2, s2, s3
	s_mul_i32 s3, s2, 0xb0
	s_sub_i32 s19, s18, s3
	s_lshl_b32 s33, s2, 6
	s_lshl_b32 s24, s19, 5
	s_ashr_i32 s25, s24, 31
	v_or_b32_e32 v16, s33, v2
	v_mov_b32_e32 v17, s17
	v_mul_lo_u32 v16, v16, v17
	s_lshl_b32 s4, s24, 2
	v_add_u32_e32 v16, s4, v16
	v_mov_b32_e32 v17, 0
	v_lshl_add_u64 v[18:19], v[10:11], 0, v[16:17]
	v_lshl_add_u64 v[20:21], v[14:15], 0, v[16:17]
	global_load_dword v60, v[18:19], off
	v_lshl_add_u64 v[18:19], v[18:19], 0, s[20:21]
	global_load_dword v61, v[18:19], off
	v_lshl_add_u64 v[18:19], v[18:19], 0, s[20:21]
	global_load_dword v62, v[18:19], off
	v_lshl_add_u64 v[18:19], v[18:19], 0, s[20:21]
	global_load_dword v63, v[18:19], off
	v_lshl_add_u64 v[18:19], v[18:19], 0, s[20:21]
	global_load_dword v64, v[18:19], off
	v_lshl_add_u64 v[18:19], v[18:19], 0, s[20:21]
	global_load_dword v65, v[18:19], off
	v_lshl_add_u64 v[18:19], v[18:19], 0, s[20:21]
	global_load_dword v66, v[18:19], off
	v_lshl_add_u64 v[18:19], v[18:19], 0, s[20:21]
	global_load_dword v67, v[18:19], off
	v_lshl_add_u64 v[18:19], v[18:19], 0, s[20:21]
	global_load_dword v68, v[18:19], off
	v_lshl_add_u64 v[18:19], v[18:19], 0, s[20:21]
	global_load_dword v69, v[18:19], off
	v_lshl_add_u64 v[18:19], v[18:19], 0, s[20:21]
	global_load_dword v70, v[18:19], off
	v_lshl_add_u64 v[18:19], v[18:19], 0, s[20:21]
	global_load_dword v71, v[18:19], off
	v_lshl_add_u64 v[18:19], v[18:19], 0, s[20:21]
	global_load_dword v72, v[18:19], off
	v_lshl_add_u64 v[18:19], v[18:19], 0, s[20:21]
	global_load_dword v73, v[18:19], off
	v_lshl_add_u64 v[18:19], v[18:19], 0, s[20:21]
	global_load_dword v74, v[18:19], off
	v_lshl_add_u64 v[18:19], v[18:19], 0, s[20:21]
	global_load_dword v75, v[18:19], off
	v_lshl_add_u64 v[18:19], v[18:19], 0, s[20:21]
	global_load_dword v76, v[18:19], off
	v_lshl_add_u64 v[18:19], v[18:19], 0, s[20:21]
	global_load_dword v77, v[18:19], off
	v_lshl_add_u64 v[18:19], v[18:19], 0, s[20:21]
	global_load_dword v78, v[18:19], off
	v_lshl_add_u64 v[18:19], v[18:19], 0, s[20:21]
	global_load_dword v79, v[18:19], off
	v_lshl_add_u64 v[18:19], v[18:19], 0, s[20:21]
	global_load_dword v80, v[18:19], off
	v_lshl_add_u64 v[18:19], v[18:19], 0, s[20:21]
	global_load_dword v81, v[18:19], off
	v_lshl_add_u64 v[18:19], v[18:19], 0, s[20:21]
	global_load_dword v82, v[18:19], off
	v_lshl_add_u64 v[18:19], v[18:19], 0, s[20:21]
	global_load_dword v83, v[18:19], off
	v_lshl_add_u64 v[18:19], v[18:19], 0, s[20:21]
	global_load_dword v84, v[18:19], off
	v_lshl_add_u64 v[18:19], v[18:19], 0, s[20:21]
	global_load_dword v85, v[18:19], off
	v_lshl_add_u64 v[18:19], v[18:19], 0, s[20:21]
	global_load_dword v86, v[18:19], off
	v_lshl_add_u64 v[18:19], v[18:19], 0, s[20:21]
	global_load_dword v87, v[18:19], off
	v_lshl_add_u64 v[18:19], v[18:19], 0, s[20:21]
	global_load_dword v88, v[18:19], off
	v_lshl_add_u64 v[18:19], v[18:19], 0, s[20:21]
	global_load_dword v89, v[18:19], off
	v_lshl_add_u64 v[18:19], v[18:19], 0, s[20:21]
	global_load_dword v90, v[18:19], off
	v_lshl_add_u64 v[18:19], v[18:19], 0, s[20:21]
	global_load_dword v91, v[18:19], off
	global_load_dword v92, v[20:21], off
	v_lshl_add_u64 v[20:21], v[20:21], 0, s[20:21]
	global_load_dword v93, v[20:21], off
	v_lshl_add_u64 v[20:21], v[20:21], 0, s[20:21]
	global_load_dword v94, v[20:21], off
	v_lshl_add_u64 v[20:21], v[20:21], 0, s[20:21]
	global_load_dword v95, v[20:21], off
	v_lshl_add_u64 v[20:21], v[20:21], 0, s[20:21]
	global_load_dword v96, v[20:21], off
	v_lshl_add_u64 v[20:21], v[20:21], 0, s[20:21]
	global_load_dword v97, v[20:21], off
	v_lshl_add_u64 v[20:21], v[20:21], 0, s[20:21]
	global_load_dword v98, v[20:21], off
	v_lshl_add_u64 v[20:21], v[20:21], 0, s[20:21]
	global_load_dword v99, v[20:21], off
	v_lshl_add_u64 v[20:21], v[20:21], 0, s[20:21]
	global_load_dword v100, v[20:21], off
	v_lshl_add_u64 v[20:21], v[20:21], 0, s[20:21]
	global_load_dword v101, v[20:21], off
	v_lshl_add_u64 v[20:21], v[20:21], 0, s[20:21]
	global_load_dword v102, v[20:21], off
	v_lshl_add_u64 v[20:21], v[20:21], 0, s[20:21]
	global_load_dword v103, v[20:21], off
	v_lshl_add_u64 v[20:21], v[20:21], 0, s[20:21]
	global_load_dword v104, v[20:21], off
	v_lshl_add_u64 v[20:21], v[20:21], 0, s[20:21]
	global_load_dword v105, v[20:21], off
	v_lshl_add_u64 v[20:21], v[20:21], 0, s[20:21]
	global_load_dword v106, v[20:21], off
	v_lshl_add_u64 v[20:21], v[20:21], 0, s[20:21]
	global_load_dword v107, v[20:21], off
	v_lshl_add_u64 v[20:21], v[20:21], 0, s[20:21]
	global_load_dword v108, v[20:21], off
	v_lshl_add_u64 v[20:21], v[20:21], 0, s[20:21]
	global_load_dword v109, v[20:21], off
	v_lshl_add_u64 v[20:21], v[20:21], 0, s[20:21]
	global_load_dword v110, v[20:21], off
	v_lshl_add_u64 v[20:21], v[20:21], 0, s[20:21]
	global_load_dword v111, v[20:21], off
	v_lshl_add_u64 v[20:21], v[20:21], 0, s[20:21]
	global_load_dword v112, v[20:21], off
	v_lshl_add_u64 v[20:21], v[20:21], 0, s[20:21]
	global_load_dword v113, v[20:21], off
	v_lshl_add_u64 v[20:21], v[20:21], 0, s[20:21]
	global_load_dword v114, v[20:21], off
	v_lshl_add_u64 v[20:21], v[20:21], 0, s[20:21]
	global_load_dword v115, v[20:21], off
	v_lshl_add_u64 v[20:21], v[20:21], 0, s[20:21]
	global_load_dword v116, v[20:21], off
	v_lshl_add_u64 v[20:21], v[20:21], 0, s[20:21]
	global_load_dword v117, v[20:21], off
	v_lshl_add_u64 v[20:21], v[20:21], 0, s[20:21]
	global_load_dword v118, v[20:21], off
	v_lshl_add_u64 v[20:21], v[20:21], 0, s[20:21]
	global_load_dword v119, v[20:21], off
	v_lshl_add_u64 v[20:21], v[20:21], 0, s[20:21]
	global_load_dword v120, v[20:21], off
	v_lshl_add_u64 v[20:21], v[20:21], 0, s[20:21]
	global_load_dword v121, v[20:21], off
	v_lshl_add_u64 v[20:21], v[20:21], 0, s[20:21]
	global_load_dword v122, v[20:21], off
	v_lshl_add_u64 v[20:21], v[20:21], 0, s[20:21]
	global_load_dword v123, v[20:21], off
	s_waitcnt vmcnt(32)
	v_max3_f32 v1, |v60|, |v61|, |v62|
	v_max3_f32 v1, v1, |v63|, |v64|
	v_max3_f32 v1, v1, |v65|, |v66|
	v_max3_f32 v1, v1, |v67|, |v68|
	v_max3_f32 v1, v1, |v69|, |v70|
	v_max3_f32 v1, v1, |v71|, |v72|
	v_max3_f32 v1, v1, |v73|, |v74|
	v_max3_f32 v1, v1, |v75|, |v76|
	v_max3_f32 v1, v1, |v77|, |v78|
	v_max3_f32 v1, v1, |v79|, |v80|
	v_max3_f32 v1, v1, |v81|, |v82|
	v_max3_f32 v1, v1, |v83|, |v84|
	v_max3_f32 v1, v1, |v85|, |v86|
	v_max3_f32 v1, v1, |v87|, |v88|
	v_max3_f32 v1, v1, |v89|, |v90|
	v_max_f32_e64 v1, v1, |v91|
	s_waitcnt vmcnt(0)
	v_max3_f32 v9, |v92|, |v93|, |v94|
	v_max3_f32 v9, v9, |v95|, |v96|
	v_max3_f32 v9, v9, |v97|, |v98|
	v_max3_f32 v9, v9, |v99|, |v100|
	v_max3_f32 v9, v9, |v101|, |v102|
	v_max3_f32 v9, v9, |v103|, |v104|
	v_max3_f32 v9, v9, |v105|, |v106|
	v_max3_f32 v9, v9, |v107|, |v108|
	v_max3_f32 v9, v9, |v109|, |v110|
	v_max3_f32 v9, v9, |v111|, |v112|
	v_max3_f32 v9, v9, |v113|, |v114|
	v_max3_f32 v9, v9, |v115|, |v116|
	v_max3_f32 v9, v9, |v117|, |v118|
	v_max3_f32 v9, v9, |v119|, |v120|
	v_max3_f32 v9, v9, |v121|, |v122|
	v_max_f32_e64 v9, v9, |v123|
	ds_bpermute_b32 v3, v25, v1
	ds_bpermute_b32 v5, v25, v9
	s_lshl_b32 s4, s19, 6
	s_and_b32 s4, s4, 0xffffff00
	s_and_b32 s5, s24, 0x60
	s_or_b32 s4, s4, s5
	s_ashr_i32 s5, s4, 31
	v_lshl_add_u64 v[16:17], s[4:5], 2, v[12:13]
	s_waitcnt lgkmcnt(0)
	v_max_f32_e32 v1, v1, v3
	v_max_f32_e32 v9, v9, v5
	s_and_saveexec_b64 s[2:3], vcc
	global_atomic_umax v[16:17], v1, off
	global_atomic_umax v[16:17], v9, off offset:512
	s_or_b64 exec, exec, s[2:3]
	s_add_i32 s18, s18, s10
	s_cmpk_gt_i32 s18, 0x15ff
	s_cbranch_scc0 .LBB0_8

.LBB0_118:
.LBB0_119:
	s_mov_b64 s[26:27], 0x1c000
	s_mov_b32 s17, 0xe000
	s_mul_hi_i32 s2, s18, 0x2aaaaaab
	s_lshr_b32 s3, s2, 31
	s_ashr_i32 s2, s2, 5
	s_add_i32 s2, s2, s3
	s_mul_i32 s3, s2, 0xc0
	s_sub_i32 s19, s18, s3
	s_lshl_b32 s33, s2, 6
	s_lshl_b32 s24, s19, 5
	s_ashr_i32 s25, s24, 31
	v_or_b32_e32 v16, s33, v2
	v_mov_b32_e32 v17, s17
	v_mul_lo_u32 v16, v16, v17
	s_lshl_b32 s4, s24, 2
	v_add_u32_e32 v16, s4, v16
	v_mov_b32_e32 v17, 0
	v_lshl_add_u64 v[18:19], v[10:11], 0, v[16:17]
	global_load_dword v60, v[18:19], off
	v_lshl_add_u64 v[18:19], v[18:19], 0, s[26:27]
	global_load_dword v61, v[18:19], off
	v_lshl_add_u64 v[18:19], v[18:19], 0, s[26:27]
	global_load_dword v62, v[18:19], off
	v_lshl_add_u64 v[18:19], v[18:19], 0, s[26:27]
	global_load_dword v63, v[18:19], off
	v_lshl_add_u64 v[18:19], v[18:19], 0, s[26:27]
	global_load_dword v64, v[18:19], off
	v_lshl_add_u64 v[18:19], v[18:19], 0, s[26:27]
	global_load_dword v65, v[18:19], off
	v_lshl_add_u64 v[18:19], v[18:19], 0, s[26:27]
	global_load_dword v66, v[18:19], off
	v_lshl_add_u64 v[18:19], v[18:19], 0, s[26:27]
	global_load_dword v67, v[18:19], off
	v_lshl_add_u64 v[18:19], v[18:19], 0, s[26:27]
	global_load_dword v68, v[18:19], off
	v_lshl_add_u64 v[18:19], v[18:19], 0, s[26:27]
	global_load_dword v69, v[18:19], off
	v_lshl_add_u64 v[18:19], v[18:19], 0, s[26:27]
	global_load_dword v70, v[18:19], off
	v_lshl_add_u64 v[18:19], v[18:19], 0, s[26:27]
	global_load_dword v71, v[18:19], off
	v_lshl_add_u64 v[18:19], v[18:19], 0, s[26:27]
	global_load_dword v72, v[18:19], off
	v_lshl_add_u64 v[18:19], v[18:19], 0, s[26:27]
	global_load_dword v73, v[18:19], off
	v_lshl_add_u64 v[18:19], v[18:19], 0, s[26:27]
	global_load_dword v74, v[18:19], off
	v_lshl_add_u64 v[18:19], v[18:19], 0, s[26:27]
	global_load_dword v75, v[18:19], off
	v_lshl_add_u64 v[18:19], v[18:19], 0, s[26:27]
	global_load_dword v76, v[18:19], off
	v_lshl_add_u64 v[18:19], v[18:19], 0, s[26:27]
	global_load_dword v77, v[18:19], off
	v_lshl_add_u64 v[18:19], v[18:19], 0, s[26:27]
	global_load_dword v78, v[18:19], off
	v_lshl_add_u64 v[18:19], v[18:19], 0, s[26:27]
	global_load_dword v79, v[18:19], off
	v_lshl_add_u64 v[18:19], v[18:19], 0, s[26:27]
	global_load_dword v80, v[18:19], off
	v_lshl_add_u64 v[18:19], v[18:19], 0, s[26:27]
	global_load_dword v81, v[18:19], off
	v_lshl_add_u64 v[18:19], v[18:19], 0, s[26:27]
	global_load_dword v82, v[18:19], off
	v_lshl_add_u64 v[18:19], v[18:19], 0, s[26:27]
	global_load_dword v83, v[18:19], off
	v_lshl_add_u64 v[18:19], v[18:19], 0, s[26:27]
	global_load_dword v84, v[18:19], off
	v_lshl_add_u64 v[18:19], v[18:19], 0, s[26:27]
	global_load_dword v85, v[18:19], off
	v_lshl_add_u64 v[18:19], v[18:19], 0, s[26:27]
	global_load_dword v86, v[18:19], off
	v_lshl_add_u64 v[18:19], v[18:19], 0, s[26:27]
	global_load_dword v87, v[18:19], off
	v_lshl_add_u64 v[18:19], v[18:19], 0, s[26:27]
	global_load_dword v88, v[18:19], off
	v_lshl_add_u64 v[18:19], v[18:19], 0, s[26:27]
	global_load_dword v89, v[18:19], off
	v_lshl_add_u64 v[18:19], v[18:19], 0, s[26:27]
	global_load_dword v90, v[18:19], off
	v_lshl_add_u64 v[18:19], v[18:19], 0, s[26:27]
	global_load_dword v91, v[18:19], off
	s_waitcnt vmcnt(0)
	v_max3_f32 v1, |v60|, |v61|, |v62|
	v_max3_f32 v1, v1, |v63|, |v64|
	v_max3_f32 v1, v1, |v65|, |v66|
	v_max3_f32 v1, v1, |v67|, |v68|
	v_max3_f32 v1, v1, |v69|, |v70|
	v_max3_f32 v1, v1, |v71|, |v72|
	v_max3_f32 v1, v1, |v73|, |v74|
	v_max3_f32 v1, v1, |v75|, |v76|
	v_max3_f32 v1, v1, |v77|, |v78|
	v_max3_f32 v1, v1, |v79|, |v80|
	v_max3_f32 v1, v1, |v81|, |v82|
	v_max3_f32 v1, v1, |v83|, |v84|
	v_max3_f32 v1, v1, |v85|, |v86|
	v_max3_f32 v1, v1, |v87|, |v88|
	v_max3_f32 v1, v1, |v89|, |v90|
	v_max_f32_e64 v1, v1, |v91|
	ds_bpermute_b32 v3, v33, v1
	v_lshl_add_u64 v[16:17], s[24:25], 2, v[12:13]
	s_waitcnt lgkmcnt(0)
	v_max_f32_e32 v1, v1, v3
	s_and_saveexec_b64 s[2:3], vcc
	global_atomic_umax v[16:17], v1, off
	s_or_b64 exec, exec, s[2:3]
	s_add_i32 s18, s18, s10
	s_cmpk_gt_i32 s18, 0x17ff
	s_cbranch_scc0 .LBB0_119

.LBB0_1291:
	s_or_b64 exec, exec, s[4:5]
	v_lshl_add_u32 v129, v130, 4, 0
	s_waitcnt lgkmcnt(0)
	s_barrier
	ds_read_b128 v[132:135], v129 offset:4096
	v_ashrrev_i32_e32 v131, 31, v130
	v_readlane_b32 s4, v251, 2
	v_readlane_b32 s5, v251, 3
	s_lshl_b32 s4, s14, 6
	s_waitcnt lgkmcnt(0)
	v_mov_b32_e32 v136, v133
	v_mov_b32_e32 v137, v134
	v_mov_b32_e32 v133, v135
	v_pk_add_f32 v[132:133], v[136:137], v[132:133]
	v_lshlrev_b64 v[134:135], 9, v[130:131]
	v_add_f32_e32 v129, v132, v133
	v_rcp_f32_e32 v132, v129
	v_mov_b32_e32 v129, v149
	s_mov_b32 s6, 0x7fffe0
	s_lshl_b64 s[2:3], s[2:3], 1
	v_pk_mul_f32 v[124:125], v[124:125], v[132:133] op_sel_hi:[1,0]
	v_pk_mul_f32 v[136:137], v[122:123], v[132:133] op_sel_hi:[1,0]
	v_pk_mul_f32 v[122:123], v[120:121], v[132:133] op_sel_hi:[1,0]
	v_cvt_pk_bf16_f32 v120, v124, v125
	v_lshl_add_u64 v[124:125], s[34:35], 0, v[134:135]
	v_pk_mul_f32 v[126:127], v[126:127], v[132:133] op_sel_hi:[1,0]
	v_lshl_add_u64 v[124:125], v[124:125], 0, s[4:5]
	v_cvt_pk_bf16_f32 v121, v126, v127
	v_cvt_pk_bf16_f32 v122, v122, v123
	v_cvt_pk_bf16_f32 v123, v136, v137
	v_lshl_add_u64 v[124:125], v[124:125], 0, v[128:129]
	global_store_dwordx4 v[124:125], v[120:123], off
	v_pk_mul_f32 v[118:119], v[118:119], v[132:133] op_sel_hi:[1,0]
	v_pk_mul_f32 v[116:117], v[116:117], v[132:133] op_sel_hi:[1,0]
	v_pk_mul_f32 v[120:121], v[114:115], v[132:133] op_sel_hi:[1,0]
	v_pk_mul_f32 v[114:115], v[112:113], v[132:133] op_sel_hi:[1,0]
	v_cvt_pk_bf16_f32 v112, v116, v117
	v_cvt_pk_bf16_f32 v113, v118, v119
	v_cvt_pk_bf16_f32 v114, v114, v115
	v_cvt_pk_bf16_f32 v115, v120, v121
	v_or_b32_e32 v116, 16, v130
	global_store_dwordx4 v[124:125], v[112:115], off offset:256
	v_ashrrev_i32_e32 v117, 31, v116
	s_mov_b32 s29, s5
	v_lshl_add_u32 v112, v116, 4, 0
	ds_read_b128 v[112:115], v112 offset:4096
	s_mov_b32 s12, 4
	s_waitcnt lgkmcnt(0)
	v_mov_b32_e32 v118, v113
	v_mov_b32_e32 v119, v114
	v_mov_b32_e32 v113, v115
	v_pk_add_f32 v[112:113], v[118:119], v[112:113]
	v_lshlrev_b64 v[114:115], 9, v[116:117]
	v_add_f32_e32 v112, v112, v113
	v_rcp_f32_e32 v112, v112
	s_nop 0
	v_pk_mul_f32 v[108:109], v[108:109], v[112:113] op_sel_hi:[1,0]
	v_pk_mul_f32 v[116:117], v[106:107], v[112:113] op_sel_hi:[1,0]
	v_pk_mul_f32 v[106:107], v[104:105], v[112:113] op_sel_hi:[1,0]
	v_cvt_pk_bf16_f32 v104, v108, v109
	v_lshl_add_u64 v[108:109], s[34:35], 0, v[114:115]
	v_pk_mul_f32 v[110:111], v[110:111], v[112:113] op_sel_hi:[1,0]
	v_lshl_add_u64 v[108:109], v[108:109], 0, s[4:5]
	v_cvt_pk_bf16_f32 v105, v110, v111
	v_cvt_pk_bf16_f32 v106, v106, v107
	v_cvt_pk_bf16_f32 v107, v116, v117
	v_lshl_add_u64 v[108:109], v[108:109], 0, v[128:129]
	global_store_dwordx4 v[108:109], v[104:107], off
	v_pk_mul_f32 v[102:103], v[102:103], v[112:113] op_sel_hi:[1,0]
	v_pk_mul_f32 v[100:101], v[100:101], v[112:113] op_sel_hi:[1,0]
	v_pk_mul_f32 v[104:105], v[98:99], v[112:113] op_sel_hi:[1,0]
	v_pk_mul_f32 v[98:99], v[96:97], v[112:113] op_sel_hi:[1,0]
	v_cvt_pk_bf16_f32 v96, v100, v101
	v_cvt_pk_bf16_f32 v97, v102, v103
	v_cvt_pk_bf16_f32 v98, v98, v99
	v_cvt_pk_bf16_f32 v99, v104, v105
	v_or_b32_e32 v100, 32, v130
	global_store_dwordx4 v[108:109], v[96:99], off offset:256
	v_ashrrev_i32_e32 v101, 31, v100
	s_nop 0
	v_lshl_add_u32 v96, v100, 4, 0
	ds_read_b128 v[96:99], v96 offset:4096
	s_waitcnt lgkmcnt(0)
	v_mov_b32_e32 v102, v97
	v_mov_b32_e32 v103, v98
	v_mov_b32_e32 v97, v99
	v_pk_add_f32 v[96:97], v[102:103], v[96:97]
	v_lshlrev_b64 v[98:99], 9, v[100:101]
	v_add_f32_e32 v96, v96, v97
	v_rcp_f32_e32 v96, v96
	s_nop 0
	v_pk_mul_f32 v[92:93], v[92:93], v[96:97] op_sel_hi:[1,0]
	v_pk_mul_f32 v[100:101], v[90:91], v[96:97] op_sel_hi:[1,0]
	v_pk_mul_f32 v[90:91], v[88:89], v[96:97] op_sel_hi:[1,0]
	v_cvt_pk_bf16_f32 v88, v92, v93
	v_lshl_add_u64 v[92:93], s[34:35], 0, v[98:99]
	v_pk_mul_f32 v[94:95], v[94:95], v[96:97] op_sel_hi:[1,0]
	v_lshl_add_u64 v[92:93], v[92:93], 0, s[4:5]
	v_cvt_pk_bf16_f32 v89, v94, v95
	v_cvt_pk_bf16_f32 v90, v90, v91
	v_cvt_pk_bf16_f32 v91, v100, v101
	v_lshl_add_u64 v[92:93], v[92:93], 0, v[128:129]
	global_store_dwordx4 v[92:93], v[88:91], off
	v_pk_mul_f32 v[86:87], v[86:87], v[96:97] op_sel_hi:[1,0]
	v_pk_mul_f32 v[84:85], v[84:85], v[96:97] op_sel_hi:[1,0]
	v_pk_mul_f32 v[88:89], v[82:83], v[96:97] op_sel_hi:[1,0]
	v_pk_mul_f32 v[82:83], v[80:81], v[96:97] op_sel_hi:[1,0]
	v_cvt_pk_bf16_f32 v80, v84, v85
	v_cvt_pk_bf16_f32 v81, v86, v87
	v_cvt_pk_bf16_f32 v82, v82, v83
	v_cvt_pk_bf16_f32 v83, v88, v89
	v_or_b32_e32 v84, 48, v130
	global_store_dwordx4 v[92:93], v[80:83], off offset:256
	v_ashrrev_i32_e32 v85, 31, v84
	s_nop 0
	v_lshl_add_u32 v80, v84, 4, 0
	ds_read_b128 v[80:83], v80 offset:4096
	s_waitcnt lgkmcnt(0)
	v_mov_b32_e32 v86, v81
	v_mov_b32_e32 v87, v82
	v_mov_b32_e32 v81, v83
	v_pk_add_f32 v[80:81], v[86:87], v[80:81]
	v_lshlrev_b64 v[82:83], 9, v[84:85]
	v_add_f32_e32 v80, v80, v81
	v_rcp_f32_e32 v80, v80
	s_nop 0
	v_pk_mul_f32 v[76:77], v[76:77], v[80:81] op_sel_hi:[1,0]
	v_pk_mul_f32 v[84:85], v[74:75], v[80:81] op_sel_hi:[1,0]
	v_pk_mul_f32 v[74:75], v[72:73], v[80:81] op_sel_hi:[1,0]
	v_cvt_pk_bf16_f32 v72, v76, v77
	v_lshl_add_u64 v[76:77], s[34:35], 0, v[82:83]
	v_pk_mul_f32 v[78:79], v[78:79], v[80:81] op_sel_hi:[1,0]
	v_lshl_add_u64 v[76:77], v[76:77], 0, s[4:5]
	v_cvt_pk_bf16_f32 v73, v78, v79
	v_cvt_pk_bf16_f32 v74, v74, v75
	v_cvt_pk_bf16_f32 v75, v84, v85
	v_lshl_add_u64 v[76:77], v[76:77], 0, v[128:129]
	global_store_dwordx4 v[76:77], v[72:75], off
	v_pk_mul_f32 v[70:71], v[70:71], v[80:81] op_sel_hi:[1,0]
	v_pk_mul_f32 v[68:69], v[68:69], v[80:81] op_sel_hi:[1,0]
	v_pk_mul_f32 v[72:73], v[66:67], v[80:81] op_sel_hi:[1,0]
	v_pk_mul_f32 v[66:67], v[64:65], v[80:81] op_sel_hi:[1,0]
	v_cvt_pk_bf16_f32 v64, v68, v69
	v_cvt_pk_bf16_f32 v65, v70, v71
	v_cvt_pk_bf16_f32 v66, v66, v67
	v_cvt_pk_bf16_f32 v67, v72, v73
	v_add_u32_e32 v68, 0x80, v130
	global_store_dwordx4 v[76:77], v[64:67], off offset:256
	v_ashrrev_i32_e32 v69, 31, v68
	s_nop 0
	v_lshl_add_u32 v64, v68, 4, 0
	ds_read_b128 v[64:67], v64 offset:4096
	s_waitcnt lgkmcnt(0)
	v_mov_b32_e32 v70, v65
	v_mov_b32_e32 v71, v66
	v_mov_b32_e32 v65, v67
	v_pk_add_f32 v[64:65], v[70:71], v[64:65]
	v_lshlrev_b64 v[66:67], 9, v[68:69]
	v_add_f32_e32 v64, v64, v65
	v_rcp_f32_e32 v64, v64
	s_nop 0
	v_pk_mul_f32 v[60:61], v[60:61], v[64:65] op_sel_hi:[1,0]
	v_pk_mul_f32 v[68:69], v[58:59], v[64:65] op_sel_hi:[1,0]
	v_pk_mul_f32 v[58:59], v[56:57], v[64:65] op_sel_hi:[1,0]
	v_cvt_pk_bf16_f32 v56, v60, v61
	v_lshl_add_u64 v[60:61], s[34:35], 0, v[66:67]
	v_pk_mul_f32 v[62:63], v[62:63], v[64:65] op_sel_hi:[1,0]
	v_lshl_add_u64 v[60:61], v[60:61], 0, s[4:5]
	v_cvt_pk_bf16_f32 v57, v62, v63
	v_cvt_pk_bf16_f32 v58, v58, v59
	v_cvt_pk_bf16_f32 v59, v68, v69
	v_lshl_add_u64 v[60:61], v[60:61], 0, v[128:129]
	global_store_dwordx4 v[60:61], v[56:59], off
	v_pk_mul_f32 v[54:55], v[54:55], v[64:65] op_sel_hi:[1,0]
	v_pk_mul_f32 v[52:53], v[52:53], v[64:65] op_sel_hi:[1,0]
	v_pk_mul_f32 v[56:57], v[50:51], v[64:65] op_sel_hi:[1,0]
	v_pk_mul_f32 v[50:51], v[48:49], v[64:65] op_sel_hi:[1,0]
	v_cvt_pk_bf16_f32 v48, v52, v53
	v_cvt_pk_bf16_f32 v49, v54, v55
	v_cvt_pk_bf16_f32 v50, v50, v51
	v_cvt_pk_bf16_f32 v51, v56, v57
	v_add_u32_e32 v52, 0x90, v130
	global_store_dwordx4 v[60:61], v[48:51], off offset:256
	v_ashrrev_i32_e32 v53, 31, v52
	s_nop 0
	v_lshl_add_u32 v48, v52, 4, 0
	ds_read_b128 v[48:51], v48 offset:4096
	s_waitcnt lgkmcnt(0)
	v_mov_b32_e32 v54, v49
	v_mov_b32_e32 v55, v50
	v_mov_b32_e32 v49, v51
	v_pk_add_f32 v[48:49], v[54:55], v[48:49]
	v_lshlrev_b64 v[50:51], 9, v[52:53]
	v_add_f32_e32 v48, v48, v49
	v_rcp_f32_e32 v48, v48
	s_nop 0
	v_pk_mul_f32 v[44:45], v[44:45], v[48:49] op_sel_hi:[1,0]
	v_pk_mul_f32 v[52:53], v[42:43], v[48:49] op_sel_hi:[1,0]
	v_pk_mul_f32 v[42:43], v[40:41], v[48:49] op_sel_hi:[1,0]
	v_cvt_pk_bf16_f32 v40, v44, v45
	v_lshl_add_u64 v[44:45], s[34:35], 0, v[50:51]
	v_pk_mul_f32 v[46:47], v[46:47], v[48:49] op_sel_hi:[1,0]
	v_lshl_add_u64 v[44:45], v[44:45], 0, s[4:5]
	v_cvt_pk_bf16_f32 v41, v46, v47
	v_cvt_pk_bf16_f32 v42, v42, v43
	v_cvt_pk_bf16_f32 v43, v52, v53
	v_lshl_add_u64 v[44:45], v[44:45], 0, v[128:129]
	global_store_dwordx4 v[44:45], v[40:43], off
	v_pk_mul_f32 v[38:39], v[38:39], v[48:49] op_sel_hi:[1,0]
	v_pk_mul_f32 v[36:37], v[36:37], v[48:49] op_sel_hi:[1,0]
	v_pk_mul_f32 v[40:41], v[34:35], v[48:49] op_sel_hi:[1,0]
	v_pk_mul_f32 v[34:35], v[32:33], v[48:49] op_sel_hi:[1,0]
	v_cvt_pk_bf16_f32 v32, v36, v37
	v_cvt_pk_bf16_f32 v33, v38, v39
	v_cvt_pk_bf16_f32 v34, v34, v35
	v_cvt_pk_bf16_f32 v35, v40, v41
	v_add_u32_e32 v36, 0xa0, v130
	global_store_dwordx4 v[44:45], v[32:35], off offset:256
	v_ashrrev_i32_e32 v37, 31, v36
	s_nop 0
	v_lshl_add_u32 v32, v36, 4, 0
	ds_read_b128 v[32:35], v32 offset:4096
	s_waitcnt lgkmcnt(0)
	v_mov_b32_e32 v38, v33
	v_mov_b32_e32 v39, v34
	v_mov_b32_e32 v33, v35
	v_pk_add_f32 v[32:33], v[38:39], v[32:33]
	v_lshlrev_b64 v[34:35], 9, v[36:37]
	v_add_f32_e32 v32, v32, v33
	v_rcp_f32_e32 v32, v32
	s_nop 0
	v_pk_mul_f32 v[28:29], v[28:29], v[32:33] op_sel_hi:[1,0]
	v_pk_mul_f32 v[36:37], v[26:27], v[32:33] op_sel_hi:[1,0]
	v_pk_mul_f32 v[26:27], v[24:25], v[32:33] op_sel_hi:[1,0]
	v_cvt_pk_bf16_f32 v24, v28, v29
	v_lshl_add_u64 v[28:29], s[34:35], 0, v[34:35]
	v_pk_mul_f32 v[30:31], v[30:31], v[32:33] op_sel_hi:[1,0]
	v_lshl_add_u64 v[28:29], v[28:29], 0, s[4:5]
	v_cvt_pk_bf16_f32 v25, v30, v31
	v_cvt_pk_bf16_f32 v26, v26, v27
	v_cvt_pk_bf16_f32 v27, v36, v37
	v_lshl_add_u64 v[28:29], v[28:29], 0, v[128:129]
	global_store_dwordx4 v[28:29], v[24:27], off
	v_pk_mul_f32 v[22:23], v[22:23], v[32:33] op_sel_hi:[1,0]
	v_pk_mul_f32 v[20:21], v[20:21], v[32:33] op_sel_hi:[1,0]
	v_pk_mul_f32 v[24:25], v[18:19], v[32:33] op_sel_hi:[1,0]
	v_pk_mul_f32 v[18:19], v[16:17], v[32:33] op_sel_hi:[1,0]
	v_cvt_pk_bf16_f32 v16, v20, v21
	v_cvt_pk_bf16_f32 v17, v22, v23
	v_cvt_pk_bf16_f32 v18, v18, v19
	v_cvt_pk_bf16_f32 v19, v24, v25
	v_add_u32_e32 v20, 0xb0, v130
	global_store_dwordx4 v[28:29], v[16:19], off offset:256
	v_ashrrev_i32_e32 v21, 31, v20
	s_nop 0
	v_lshl_add_u32 v16, v20, 4, 0
	ds_read_b128 v[16:19], v16 offset:4096
	s_waitcnt lgkmcnt(0)
	v_mov_b32_e32 v22, v17
	v_mov_b32_e32 v23, v18
	v_mov_b32_e32 v17, v19
	v_pk_add_f32 v[16:17], v[22:23], v[16:17]
	v_lshlrev_b64 v[18:19], 9, v[20:21]
	v_add_f32_e32 v16, v16, v17
	v_rcp_f32_e32 v16, v16
	s_nop 0
	v_pk_mul_f32 v[12:13], v[12:13], v[16:17] op_sel_hi:[1,0]
	v_pk_mul_f32 v[20:21], v[10:11], v[16:17] op_sel_hi:[1,0]
	v_pk_mul_f32 v[10:11], v[8:9], v[16:17] op_sel_hi:[1,0]
	v_cvt_pk_bf16_f32 v8, v12, v13
	v_lshl_add_u64 v[12:13], s[34:35], 0, v[18:19]
	v_pk_mul_f32 v[14:15], v[14:15], v[16:17] op_sel_hi:[1,0]
	v_lshl_add_u64 v[12:13], v[12:13], 0, s[4:5]
	v_cvt_pk_bf16_f32 v9, v14, v15
	v_cvt_pk_bf16_f32 v10, v10, v11
	v_cvt_pk_bf16_f32 v11, v20, v21
	v_lshl_add_u64 v[12:13], v[12:13], 0, v[128:129]
	global_store_dwordx4 v[12:13], v[8:11], off
	v_pk_mul_f32 v[6:7], v[6:7], v[16:17] op_sel_hi:[1,0]
	v_pk_mul_f32 v[4:5], v[4:5], v[16:17] op_sel_hi:[1,0]
	v_pk_mul_f32 v[8:9], v[2:3], v[16:17] op_sel_hi:[1,0]
	v_pk_mul_f32 v[2:3], v[0:1], v[16:17] op_sel_hi:[1,0]
	v_cvt_pk_bf16_f32 v0, v4, v5
	v_cvt_pk_bf16_f32 v1, v6, v7
	v_cvt_pk_bf16_f32 v2, v2, v3
	v_cvt_pk_bf16_f32 v3, v8, v9
	global_store_dwordx4 v[12:13], v[0:3], off offset:256
	s_barrier
	s_nop 0
	v_mov_b32_e32 v3, v190
	s_waitcnt vmcnt(0)
	buffer_inv sc1
	s_barrier
	v_readlane_b32 s4, v253, 42
	v_lshlrev_b32_e32 v4, 4, v3
	v_add_u32_e32 v1, 0x2000, v4
	v_ashrrev_i32_e32 v0, 31, v1
	v_lshrrev_b32_e32 v0, 22, v0
	v_add_u32_e32 v0, v1, v0
	v_ashrrev_i32_e32 v0, 10, v0
	v_mul_i32_i24_e32 v2, 0x400, v0
	v_sub_u32_e32 v1, v1, v2
	v_lshrrev_b32_e32 v2, 4, v1
	v_bitop3_b32 v2, v2, v1, 32 bitop3:0x6c
	v_ashrrev_i32_e32 v1, 31, v2
	v_lshrrev_b32_e32 v1, 26, v1
	v_add_u32_e32 v5, v2, v1
	v_lshlrev_b32_e32 v6, 3, v0
	v_ashrrev_i32_e32 v1, 6, v5
	v_and_b32_e32 v6, -16, v6
	v_add_u32_e32 v6, v1, v6
	v_and_b32_e32 v7, 3, v1
	v_lshrrev_b32_e32 v8, 2, v6
	v_lshlrev_b32_e32 v9, 1, v6
	v_and_b32_e32 v5, 0xc0, v5
	v_and_or_b32 v7, v6, s6, v7
	v_and_b32_e32 v8, 4, v8
	v_and_b32_e32 v9, 24, v9
	v_sub_u32_e32 v2, v2, v5
	v_or3_b32 v7, v7, v8, v9
	v_lshlrev_b32_e32 v8, 5, v0
	v_ashrrev_i16_sdwa v2, v194, sext(v2) dst_sel:DWORD dst_unused:UNUSED_PAD src0_sel:DWORD src1_sel:BYTE_0
	v_and_b32_e32 v8, 32, v8
	v_bfe_i32 v2, v2, 0, 16
	v_add_lshl_u32 v5, v8, v2, 1
	v_lshl_add_u32 v132, v7, 9, v5
	v_lshl_add_u32 v134, v6, 9, v5
	v_bfe_i32 v5, v3, 27, 1
	v_lshrrev_b32_e32 v5, 22, v5
	v_add_u32_e32 v5, v4, v5
	v_and_b32_e32 v5, 0xfffffc00, v5
	v_sub_u32_e32 v4, v4, v5
	v_lshrrev_b32_e32 v5, 4, v4
	v_bitop3_b32 v6, v5, v4, 32 bitop3:0x6c
	v_ashrrev_i32_e32 v5, 31, v3
	v_lshrrev_b32_e32 v5, 26, v5
	v_ashrrev_i32_e32 v4, 31, v6
	v_add_u32_e32 v5, v3, v5
	v_lshrrev_b32_e32 v4, 26, v4
	v_ashrrev_i32_e32 v5, 6, v5
	v_add_u32_e32 v7, v6, v4
	v_lshlrev_b32_e32 v8, 3, v5
	v_ashrrev_i32_e32 v4, 6, v7
	v_and_b32_e32 v8, -16, v8
	v_add_u32_e32 v8, v4, v8
	v_and_b32_e32 v9, 3, v4
	v_lshrrev_b32_e32 v10, 2, v8
	v_lshlrev_b32_e32 v11, 1, v8
	v_and_b32_e32 v7, 0xc0, v7
	s_add_u32 s2, s4, s2
	v_readlane_b32 s4, v253, 43
	v_readfirstlane_b32 s10, v3
	v_and_or_b32 v9, v8, s6, v9
	v_and_b32_e32 v10, 4, v10
	v_and_b32_e32 v11, 24, v11
	v_sub_u32_e32 v6, v6, v7
	s_addc_u32 s3, s4, s3
	s_ashr_i32 s5, s10, 6
	v_or3_b32 v9, v9, v10, v11
	v_lshlrev_b32_e32 v10, 5, v5
	v_ashrrev_i16_sdwa v6, v194, sext(v6) dst_sel:DWORD dst_unused:UNUSED_PAD src0_sel:DWORD src1_sel:BYTE_0
	s_lshl_b32 s13, s5, 10
	v_and_b32_e32 v10, 32, v10
	v_bfe_i32 v6, v6, 0, 16
	v_add_lshl_u32 v7, v10, v6, 1
	s_add_i32 s14, s13, 0
	v_lshl_add_u32 v148, v9, 9, v7
	s_add_i32 m0, s14, 0x10000
	s_ashr_i32 s4, s10, 8
	global_load_lds_dwordx4 v148, s[2:3]
	s_add_i32 m0, s14, 0x12000
	s_add_u32 s6, s2, 0x10000
	global_load_lds_dwordx4 v132, s[2:3]
	s_addc_u32 s7, s3, 0
	s_add_i32 m0, s14, 0x14000
	v_lshl_add_u32 v136, v8, 9, v7
	global_load_lds_dwordx4 v148, s[6:7]
	s_add_i32 m0, s14, 0x16000
	s_add_i32 s15, s14, 0x2000
	global_load_lds_dwordx4 v132, s[6:7]
	s_mov_b32 m0, s14
	s_add_i32 s16, s14, 0x4000
	global_load_lds_dwordx4 v136, s[34:35]
	s_mov_b32 m0, s15
	v_readlane_b32 s6, v253, 46
	global_load_lds_dwordx4 v134, s[34:35]
	s_mov_b32 m0, s16
	v_readlane_b32 s7, v253, 47
	s_add_i32 s17, s14, 0x6000
	s_cmp_lg_u32 s4, 1
	s_nop 2
	global_load_lds_dwordx4 v136, s[6:7]
	s_mov_b32 m0, s17
	s_nop 0
	global_load_lds_dwordx4 v134, s[6:7]
	s_cbranch_scc1 .LBB0_1293
	s_barrier
